# v009 + merge loops (P3,P5) unrolled x2: 12 loads in flight before one vmcnt(0) (counted-wait / double-buffer lever on the streaming merge)
# speedup vs baseline: 1.0003x; 1.0003x over previous
; __device__ __forceinline__ unsigned cvtpk(float lo, float hi) { return pg8::cvt_pk_bf16(lo, hi); }
; __device__ __forceinline__ float bflo(unsigned u) { return __uint_as_float(u << 16); }
; __device__ __forceinline__ float bfhi(unsigned u) { return __uint_as_float(u & 0xffff0000u); }
; __device__ __forceinline__ void merge_half(const bf16* __restrict__ Og, const float* __restrict__ L2, bf16* __restrict__ O  , int gtid, int gthreads) {
;     for (int idx = gtid; idx < MH * 128; idx += gthreads) {
;         const int tl = idx >> 7, ch = idx & 127, h = ch >> 4;
;         const float l0 = L2[((size_t)0 * MH + tl) * 8 + h], l1 = L2[((size_t)1 * MH + tl) * 8 + h], l2 = L2[((size_t)2 * MH + tl) * 8 + h];
;         const float mx = fmaxf(l0, fmaxf(l1, l2));
;         float w0 = __builtin_amdgcn_exp2f(l0 - mx), w1 = __builtin_amdgcn_exp2f(l1 - mx), w2 = __builtin_amdgcn_exp2f(l2 - mx);
;         const float inv = __builtin_amdgcn_rcpf(w0 + w1 + w2); w0 *= inv; w1 *= inv; w2 *= inv;
;         const v4u a = __builtin_nontemporal_load((const v4u*)(Og + ((size_t)0 * MH + tl) * 1024 + ch * 8)), b = __builtin_nontemporal_load((const v4u*)(Og + ((size_t)1 * MH + tl) * 1024 + ch * 8)), c = __builtin_nontemporal_load((const v4u*)(Og + ((size_t)2 * MH + tl) * 1024 + ch * 8));
;         v4u o;
; #pragma unroll
;         for (int j = 0; j < 4; ++j) o[j] = cvtpk(w0 * bflo(a[j]) + w1 * bflo(b[j]) + w2 * bflo(c[j]), w0 * bfhi(a[j]) + w1 * bfhi(b[j]) + w2 * bfhi(c[j]));
;         __builtin_nontemporal_store(o, (v4u*)(O + (size_t)tl * 1024 + ch * 8));
;     }
.LBB0_359:
	v_ashrrev_i32_e32 v8, 7, v6
	v_ashrrev_i32_e32 v9, 31, v8
	v_lshl_add_u64 v[12:13], v[8:9], 0, s[4:5]
	v_lshlrev_b64 v[10:11], 5, v[8:9]
	v_lshl_add_u64 v[14:15], v[8:9], 0, s[8:9]
	v_lshlrev_b64 v[20:21], 11, v[8:9]
	v_lshlrev_b64 v[18:19], 5, v[12:13]
	v_lshlrev_b64 v[12:13], 11, v[12:13]
	v_lshl_add_u64 v[16:17], v[0:1], 0, v[10:11]
	v_lshlrev_b64 v[22:23], 5, v[14:15]
	v_lshl_add_u64 v[8:9], v[2:3], 0, v[20:21]
	v_lshlrev_b64 v[14:15], 11, v[14:15]
	v_lshl_add_u64 v[18:19], v[0:1], 0, v[18:19]
	v_lshl_add_u64 v[12:13], v[2:3], 0, v[12:13]
	global_load_dwordx4 v[8:11], v[8:9], off nt
	v_lshl_add_u64 v[22:23], v[0:1], 0, v[22:23]
	v_lshl_add_u64 v[24:25], v[2:3], 0, v[14:15]
	global_load_dword v7, v[16:17], off
	global_load_dword v36, v[18:19], off
	global_load_dword v37, v[22:23], off
	s_nop 0
	global_load_dwordx4 v[12:15], v[12:13], off nt
	s_nop 0
	global_load_dwordx4 v[16:19], v[24:25], off nt
	v_lshl_add_u64 v[20:21], v[4:5], 0, v[20:21]
	v_add_u32_e32 v46, s11, v6
	v_cmp_ge_i32_e32 vcc, s10, v46
	s_mov_b64 s[98:99], exec
	s_and_b64 exec, exec, vcc
	v_ashrrev_i32_e32 v48, 7, v46
	v_ashrrev_i32_e32 v49, 31, v48
	v_lshl_add_u64 v[52:53], v[48:49], 0, s[4:5]
	v_lshlrev_b64 v[50:51], 5, v[48:49]
	v_lshl_add_u64 v[54:55], v[48:49], 0, s[8:9]
	v_lshlrev_b64 v[60:61], 11, v[48:49]
	v_lshlrev_b64 v[58:59], 5, v[52:53]
	v_lshlrev_b64 v[52:53], 11, v[52:53]
	v_lshl_add_u64 v[56:57], v[0:1], 0, v[50:51]
	v_lshlrev_b64 v[62:63], 5, v[54:55]
	v_lshl_add_u64 v[48:49], v[2:3], 0, v[60:61]
	v_lshlrev_b64 v[54:55], 11, v[54:55]
	v_lshl_add_u64 v[58:59], v[0:1], 0, v[58:59]
	v_lshl_add_u64 v[52:53], v[2:3], 0, v[52:53]
	global_load_dwordx4 v[48:51], v[48:49], off nt
	v_lshl_add_u64 v[62:63], v[0:1], 0, v[62:63]
	v_lshl_add_u64 v[64:65], v[2:3], 0, v[54:55]
	global_load_dword v47, v[56:57], off
	global_load_dword v76, v[58:59], off
	global_load_dword v77, v[62:63], off
	s_nop 0
	global_load_dwordx4 v[52:55], v[52:53], off nt
	s_nop 0
	global_load_dwordx4 v[56:59], v[64:65], off nt
	v_lshl_add_u64 v[60:61], v[4:5], 0, v[60:61]
	s_mov_b64 exec, s[98:99]
	v_add_u32_e32 v6, s11, v46
	v_cmp_lt_i32_e32 vcc, s10, v6
	s_or_b64 s[2:3], vcc, s[2:3]
	s_waitcnt vmcnt(0)
	v_and_b32_e32 v25, 0xffff0000, v9
	v_max3_f32 v38, v7, v36, v37
	v_lshlrev_b32_e32 v26, 16, v9
	v_lshlrev_b32_e32 v22, 16, v12
	v_and_b32_e32 v9, 0xffff0000, v12
	v_lshlrev_b32_e32 v34, 16, v16
	v_and_b32_e32 v35, 0xffff0000, v16
	v_lshlrev_b32_e32 v24, 16, v13
	v_and_b32_e32 v27, 0xffff0000, v13
	v_lshlrev_b32_e32 v12, 16, v17
	v_and_b32_e32 v13, 0xffff0000, v17
	v_lshlrev_b32_e32 v16, 16, v18
	v_and_b32_e32 v17, 0xffff0000, v18
	v_sub_f32_e32 v7, v7, v38
	v_sub_f32_e32 v18, v36, v38
	v_and_b32_e32 v31, 0xffff0000, v11
	v_lshlrev_b32_e32 v32, 16, v11
	v_lshlrev_b32_e32 v28, 16, v14
	v_and_b32_e32 v11, 0xffff0000, v14
	v_lshlrev_b32_e32 v30, 16, v15
	v_and_b32_e32 v33, 0xffff0000, v15
	v_lshlrev_b32_e32 v14, 16, v19
	v_and_b32_e32 v15, 0xffff0000, v19
	v_sub_f32_e32 v36, v37, v38
	v_exp_f32_e32 v19, v7
	v_exp_f32_e32 v18, v18
	v_exp_f32_e32 v7, v36
	v_and_b32_e32 v23, 0xffff0000, v8
	v_lshlrev_b32_e32 v8, 16, v8
	v_add_f32_e32 v36, v19, v18
	v_add_f32_e32 v36, v7, v36
	v_rcp_f32_e32 v36, v36
	v_and_b32_e32 v29, 0xffff0000, v10
	v_lshlrev_b32_e32 v10, 16, v10
	v_pk_mul_f32 v[18:19], v[18:19], v[36:37] op_sel_hi:[1,0]
	s_nop 0
	v_pk_mul_f32 v[8:9], v[18:19], v[8:9] op_sel:[1,0] op_sel_hi:[0,1]
	v_pk_mul_f32 v[26:27], v[18:19], v[26:27] op_sel:[1,0] op_sel_hi:[0,1]
	v_pk_mul_f32 v[10:11], v[18:19], v[10:11] op_sel:[1,0] op_sel_hi:[0,1]
	v_pk_mul_f32 v[32:33], v[18:19], v[32:33] op_sel:[1,0] op_sel_hi:[0,1]
	v_mul_f32_e32 v38, v7, v36
	v_pk_fma_f32 v[8:9], v[18:19], v[22:23], v[8:9]
	v_pk_fma_f32 v[22:23], v[18:19], v[24:25], v[26:27]
	v_pk_fma_f32 v[10:11], v[18:19], v[28:29], v[10:11]
	v_pk_fma_f32 v[18:19], v[18:19], v[30:31], v[32:33]
	v_pk_fma_f32 v[8:9], v[38:39], v[34:35], v[8:9] op_sel_hi:[0,1,1]
	v_pk_fma_f32 v[12:13], v[38:39], v[12:13], v[22:23] op_sel_hi:[0,1,1]
	v_pk_fma_f32 v[10:11], v[38:39], v[16:17], v[10:11] op_sel_hi:[0,1,1]
	v_pk_fma_f32 v[14:15], v[38:39], v[14:15], v[18:19] op_sel_hi:[0,1,1]
	v_cvt_pk_bf16_f32 v8, v8, v9
	v_cvt_pk_bf16_f32 v9, v12, v13
	v_cvt_pk_bf16_f32 v10, v10, v11
	v_cvt_pk_bf16_f32 v11, v14, v15
	global_store_dwordx4 v[20:21], v[8:11], off nt
	v_and_b32_e32 v65, 0xffff0000, v49
	v_max3_f32 v78, v47, v76, v77
	v_lshlrev_b32_e32 v66, 16, v49
	v_lshlrev_b32_e32 v62, 16, v52
	v_and_b32_e32 v49, 0xffff0000, v52
	v_lshlrev_b32_e32 v74, 16, v56
	v_and_b32_e32 v75, 0xffff0000, v56
	v_lshlrev_b32_e32 v64, 16, v53
	v_and_b32_e32 v67, 0xffff0000, v53
	v_lshlrev_b32_e32 v52, 16, v57
	v_and_b32_e32 v53, 0xffff0000, v57
	v_lshlrev_b32_e32 v56, 16, v58
	v_and_b32_e32 v57, 0xffff0000, v58
	v_sub_f32_e32 v47, v47, v78
	v_sub_f32_e32 v58, v76, v78
	v_and_b32_e32 v71, 0xffff0000, v51
	v_lshlrev_b32_e32 v72, 16, v51
	v_lshlrev_b32_e32 v68, 16, v54
	v_and_b32_e32 v51, 0xffff0000, v54
	v_lshlrev_b32_e32 v70, 16, v55
	v_and_b32_e32 v73, 0xffff0000, v55
	v_lshlrev_b32_e32 v54, 16, v59
	v_and_b32_e32 v55, 0xffff0000, v59
	v_sub_f32_e32 v76, v77, v78
	v_exp_f32_e32 v59, v47
	v_exp_f32_e32 v58, v58
	v_exp_f32_e32 v47, v76
	v_and_b32_e32 v63, 0xffff0000, v48
	v_lshlrev_b32_e32 v48, 16, v48
	v_add_f32_e32 v76, v59, v58
	v_add_f32_e32 v76, v47, v76
	v_rcp_f32_e32 v76, v76
	v_and_b32_e32 v69, 0xffff0000, v50
	v_lshlrev_b32_e32 v50, 16, v50
	v_pk_mul_f32 v[58:59], v[58:59], v[76:77] op_sel_hi:[1,0]
	s_nop 0
	v_pk_mul_f32 v[48:49], v[58:59], v[48:49] op_sel:[1,0] op_sel_hi:[0,1]
	v_pk_mul_f32 v[66:67], v[58:59], v[66:67] op_sel:[1,0] op_sel_hi:[0,1]
	v_pk_mul_f32 v[50:51], v[58:59], v[50:51] op_sel:[1,0] op_sel_hi:[0,1]
	v_pk_mul_f32 v[72:73], v[58:59], v[72:73] op_sel:[1,0] op_sel_hi:[0,1]
	v_mul_f32_e32 v78, v47, v76
	v_pk_fma_f32 v[48:49], v[58:59], v[62:63], v[48:49]
	v_pk_fma_f32 v[62:63], v[58:59], v[64:65], v[66:67]
	v_pk_fma_f32 v[50:51], v[58:59], v[68:69], v[50:51]
	v_pk_fma_f32 v[58:59], v[58:59], v[70:71], v[72:73]
	v_pk_fma_f32 v[48:49], v[78:79], v[74:75], v[48:49] op_sel_hi:[0,1,1]
	v_pk_fma_f32 v[52:53], v[78:79], v[52:53], v[62:63] op_sel_hi:[0,1,1]
	v_pk_fma_f32 v[50:51], v[78:79], v[56:57], v[50:51] op_sel_hi:[0,1,1]
	v_pk_fma_f32 v[54:55], v[78:79], v[54:55], v[58:59] op_sel_hi:[0,1,1]
	v_cvt_pk_bf16_f32 v48, v48, v49
	v_cvt_pk_bf16_f32 v49, v52, v53
	v_cvt_pk_bf16_f32 v50, v50, v51
	v_cvt_pk_bf16_f32 v51, v54, v55
	v_cmp_ge_i32_e32 vcc, s10, v46
	s_and_b64 exec, exec, vcc
	global_store_dwordx4 v[60:61], v[48:51], off nt
	s_mov_b64 exec, s[98:99]
	s_andn2_b64 exec, exec, s[2:3]
	s_cbranch_execnz .LBB0_359

; __device__ __forceinline__ unsigned cvtpk(float lo, float hi) { return pg8::cvt_pk_bf16(lo, hi); }
; __device__ __forceinline__ float bflo(unsigned u) { return __uint_as_float(u << 16); }
; __device__ __forceinline__ float bfhi(unsigned u) { return __uint_as_float(u & 0xffff0000u); }
; __device__ __forceinline__ void merge_half(const bf16* __restrict__ Og, const float* __restrict__ L2, bf16* __restrict__ O  , int gtid, int gthreads) {
;     for (int idx = gtid; idx < MH * 128; idx += gthreads) {
;         const int tl = idx >> 7, ch = idx & 127, h = ch >> 4;
;         const float l0 = L2[((size_t)0 * MH + tl) * 8 + h], l1 = L2[((size_t)1 * MH + tl) * 8 + h], l2 = L2[((size_t)2 * MH + tl) * 8 + h];
;         const float mx = fmaxf(l0, fmaxf(l1, l2));
;         float w0 = __builtin_amdgcn_exp2f(l0 - mx), w1 = __builtin_amdgcn_exp2f(l1 - mx), w2 = __builtin_amdgcn_exp2f(l2 - mx);
;         const float inv = __builtin_amdgcn_rcpf(w0 + w1 + w2); w0 *= inv; w1 *= inv; w2 *= inv;
;         const v4u a = __builtin_nontemporal_load((const v4u*)(Og + ((size_t)0 * MH + tl) * 1024 + ch * 8)), b = __builtin_nontemporal_load((const v4u*)(Og + ((size_t)1 * MH + tl) * 1024 + ch * 8)), c = __builtin_nontemporal_load((const v4u*)(Og + ((size_t)2 * MH + tl) * 1024 + ch * 8));
;         v4u o;
; #pragma unroll
;         for (int j = 0; j < 4; ++j) o[j] = cvtpk(w0 * bflo(a[j]) + w1 * bflo(b[j]) + w2 * bflo(c[j]), w0 * bfhi(a[j]) + w1 * bfhi(b[j]) + w2 * bfhi(c[j]));
;         __builtin_nontemporal_store(o, (v4u*)(O + (size_t)tl * 1024 + ch * 8));
;     }
.LBB0_513:
	v_ashrrev_i32_e32 v8, 7, v6
	v_ashrrev_i32_e32 v9, 31, v8
	v_lshlrev_b64 v[10:11], 5, v[8:9]
	v_lshl_add_u64 v[12:13], v[8:9], 0, s[6:7]
	v_lshl_add_u64 v[14:15], v[8:9], 0, s[8:9]
	v_lshlrev_b64 v[20:21], 11, v[8:9]
	v_lshl_add_u64 v[22:23], v[0:1], 0, v[10:11]
	v_lshlrev_b64 v[16:17], 5, v[12:13]
	v_lshlrev_b64 v[18:19], 5, v[14:15]
	v_lshl_add_u64 v[8:9], v[2:3], 0, v[20:21]
	v_lshlrev_b64 v[12:13], 11, v[12:13]
	v_lshlrev_b64 v[14:15], 11, v[14:15]
	global_load_dwordx4 v[8:11], v[8:9], off nt
	v_lshl_add_u64 v[24:25], v[0:1], 0, v[16:17]
	v_lshl_add_u64 v[26:27], v[0:1], 0, v[18:19]
	v_lshl_add_u64 v[28:29], v[2:3], 0, v[12:13]
	v_lshl_add_u64 v[30:31], v[2:3], 0, v[14:15]
	global_load_dword v7, v[22:23], off
	global_load_dword v36, v[24:25], off
	global_load_dword v37, v[26:27], off
	global_load_dwordx4 v[12:15], v[28:29], off nt
	global_load_dwordx4 v[16:19], v[30:31], off nt
	v_lshl_add_u64 v[20:21], v[4:5], 0, v[20:21]
	v_add_u32_e32 v46, s11, v6
	v_cmp_ge_i32_e32 vcc, s10, v46
	s_mov_b64 s[98:99], exec
	s_and_b64 exec, exec, vcc
	v_ashrrev_i32_e32 v48, 7, v46
	v_ashrrev_i32_e32 v49, 31, v48
	v_lshlrev_b64 v[50:51], 5, v[48:49]
	v_lshl_add_u64 v[52:53], v[48:49], 0, s[6:7]
	v_lshl_add_u64 v[54:55], v[48:49], 0, s[8:9]
	v_lshlrev_b64 v[60:61], 11, v[48:49]
	v_lshl_add_u64 v[62:63], v[0:1], 0, v[50:51]
	v_lshlrev_b64 v[56:57], 5, v[52:53]
	v_lshlrev_b64 v[58:59], 5, v[54:55]
	v_lshl_add_u64 v[48:49], v[2:3], 0, v[60:61]
	v_lshlrev_b64 v[52:53], 11, v[52:53]
	v_lshlrev_b64 v[54:55], 11, v[54:55]
	global_load_dwordx4 v[48:51], v[48:49], off nt
	v_lshl_add_u64 v[64:65], v[0:1], 0, v[56:57]
	v_lshl_add_u64 v[66:67], v[0:1], 0, v[58:59]
	v_lshl_add_u64 v[68:69], v[2:3], 0, v[52:53]
	v_lshl_add_u64 v[70:71], v[2:3], 0, v[54:55]
	global_load_dword v47, v[62:63], off
	global_load_dword v76, v[64:65], off
	global_load_dword v77, v[66:67], off
	global_load_dwordx4 v[52:55], v[68:69], off nt
	global_load_dwordx4 v[56:59], v[70:71], off nt
	v_lshl_add_u64 v[60:61], v[4:5], 0, v[60:61]
	s_mov_b64 exec, s[98:99]
	v_add_u32_e32 v6, s11, v46
	v_cmp_lt_i32_e32 vcc, s10, v6
	s_or_b64 s[4:5], vcc, s[4:5]
	s_waitcnt vmcnt(0)
	v_and_b32_e32 v25, 0xffff0000, v9
	v_lshlrev_b32_e32 v26, 16, v9
	v_and_b32_e32 v31, 0xffff0000, v11
	v_max3_f32 v38, v7, v36, v37
	v_lshlrev_b32_e32 v22, 16, v12
	v_and_b32_e32 v9, 0xffff0000, v12
	v_lshlrev_b32_e32 v34, 16, v16
	v_and_b32_e32 v35, 0xffff0000, v16
	v_lshlrev_b32_e32 v24, 16, v13
	v_and_b32_e32 v27, 0xffff0000, v13
	v_lshlrev_b32_e32 v12, 16, v17
	v_and_b32_e32 v13, 0xffff0000, v17
	v_lshlrev_b32_e32 v16, 16, v18
	v_and_b32_e32 v17, 0xffff0000, v18
	v_sub_f32_e32 v7, v7, v38
	v_sub_f32_e32 v18, v36, v38
	v_lshlrev_b32_e32 v32, 16, v11
	v_lshlrev_b32_e32 v28, 16, v14
	v_and_b32_e32 v11, 0xffff0000, v14
	v_lshlrev_b32_e32 v30, 16, v15
	v_and_b32_e32 v33, 0xffff0000, v15
	v_lshlrev_b32_e32 v14, 16, v19
	v_and_b32_e32 v15, 0xffff0000, v19
	v_sub_f32_e32 v36, v37, v38
	v_exp_f32_e32 v19, v7
	v_exp_f32_e32 v18, v18
	v_exp_f32_e32 v7, v36
	v_and_b32_e32 v23, 0xffff0000, v8
	v_lshlrev_b32_e32 v8, 16, v8
	v_add_f32_e32 v36, v19, v18
	v_add_f32_e32 v36, v7, v36
	v_rcp_f32_e32 v36, v36
	v_and_b32_e32 v29, 0xffff0000, v10
	v_lshlrev_b32_e32 v10, 16, v10
	v_pk_mul_f32 v[18:19], v[18:19], v[36:37] op_sel_hi:[1,0]
	s_nop 0
	v_pk_mul_f32 v[8:9], v[18:19], v[8:9] op_sel:[1,0] op_sel_hi:[0,1]
	v_pk_mul_f32 v[26:27], v[18:19], v[26:27] op_sel:[1,0] op_sel_hi:[0,1]
	v_pk_mul_f32 v[10:11], v[18:19], v[10:11] op_sel:[1,0] op_sel_hi:[0,1]
	v_pk_mul_f32 v[32:33], v[18:19], v[32:33] op_sel:[1,0] op_sel_hi:[0,1]
	v_mul_f32_e32 v38, v7, v36
	v_pk_fma_f32 v[8:9], v[18:19], v[22:23], v[8:9]
	v_pk_fma_f32 v[22:23], v[18:19], v[24:25], v[26:27]
	v_pk_fma_f32 v[10:11], v[18:19], v[28:29], v[10:11]
	v_pk_fma_f32 v[18:19], v[18:19], v[30:31], v[32:33]
	v_pk_fma_f32 v[8:9], v[38:39], v[34:35], v[8:9] op_sel_hi:[0,1,1]
	v_pk_fma_f32 v[12:13], v[38:39], v[12:13], v[22:23] op_sel_hi:[0,1,1]
	v_pk_fma_f32 v[10:11], v[38:39], v[16:17], v[10:11] op_sel_hi:[0,1,1]
	v_pk_fma_f32 v[14:15], v[38:39], v[14:15], v[18:19] op_sel_hi:[0,1,1]
	v_cvt_pk_bf16_f32 v8, v8, v9
	v_cvt_pk_bf16_f32 v9, v12, v13
	v_cvt_pk_bf16_f32 v10, v10, v11
	v_cvt_pk_bf16_f32 v11, v14, v15
	global_store_dwordx4 v[20:21], v[8:11], off nt
	v_and_b32_e32 v65, 0xffff0000, v49
	v_lshlrev_b32_e32 v66, 16, v49
	v_and_b32_e32 v71, 0xffff0000, v51
	v_max3_f32 v78, v47, v76, v77
	v_lshlrev_b32_e32 v62, 16, v52
	v_and_b32_e32 v49, 0xffff0000, v52
	v_lshlrev_b32_e32 v74, 16, v56
	v_and_b32_e32 v75, 0xffff0000, v56
	v_lshlrev_b32_e32 v64, 16, v53
	v_and_b32_e32 v67, 0xffff0000, v53
	v_lshlrev_b32_e32 v52, 16, v57
	v_and_b32_e32 v53, 0xffff0000, v57
	v_lshlrev_b32_e32 v56, 16, v58
	v_and_b32_e32 v57, 0xffff0000, v58
	v_sub_f32_e32 v47, v47, v78
	v_sub_f32_e32 v58, v76, v78
	v_lshlrev_b32_e32 v72, 16, v51
	v_lshlrev_b32_e32 v68, 16, v54
	v_and_b32_e32 v51, 0xffff0000, v54
	v_lshlrev_b32_e32 v70, 16, v55
	v_and_b32_e32 v73, 0xffff0000, v55
	v_lshlrev_b32_e32 v54, 16, v59
	v_and_b32_e32 v55, 0xffff0000, v59
	v_sub_f32_e32 v76, v77, v78
	v_exp_f32_e32 v59, v47
	v_exp_f32_e32 v58, v58
	v_exp_f32_e32 v47, v76
	v_and_b32_e32 v63, 0xffff0000, v48
	v_lshlrev_b32_e32 v48, 16, v48
	v_add_f32_e32 v76, v59, v58
	v_add_f32_e32 v76, v47, v76
	v_rcp_f32_e32 v76, v76
	v_and_b32_e32 v69, 0xffff0000, v50
	v_lshlrev_b32_e32 v50, 16, v50
	v_pk_mul_f32 v[58:59], v[58:59], v[76:77] op_sel_hi:[1,0]
	s_nop 0
	v_pk_mul_f32 v[48:49], v[58:59], v[48:49] op_sel:[1,0] op_sel_hi:[0,1]
	v_pk_mul_f32 v[66:67], v[58:59], v[66:67] op_sel:[1,0] op_sel_hi:[0,1]
	v_pk_mul_f32 v[50:51], v[58:59], v[50:51] op_sel:[1,0] op_sel_hi:[0,1]
	v_pk_mul_f32 v[72:73], v[58:59], v[72:73] op_sel:[1,0] op_sel_hi:[0,1]
	v_mul_f32_e32 v78, v47, v76
	v_pk_fma_f32 v[48:49], v[58:59], v[62:63], v[48:49]
	v_pk_fma_f32 v[62:63], v[58:59], v[64:65], v[66:67]
	v_pk_fma_f32 v[50:51], v[58:59], v[68:69], v[50:51]
	v_pk_fma_f32 v[58:59], v[58:59], v[70:71], v[72:73]
	v_pk_fma_f32 v[48:49], v[78:79], v[74:75], v[48:49] op_sel_hi:[0,1,1]
	v_pk_fma_f32 v[52:53], v[78:79], v[52:53], v[62:63] op_sel_hi:[0,1,1]
	v_pk_fma_f32 v[50:51], v[78:79], v[56:57], v[50:51] op_sel_hi:[0,1,1]
	v_pk_fma_f32 v[54:55], v[78:79], v[54:55], v[58:59] op_sel_hi:[0,1,1]
	v_cvt_pk_bf16_f32 v48, v48, v49
	v_cvt_pk_bf16_f32 v49, v52, v53
	v_cvt_pk_bf16_f32 v50, v50, v51
	v_cvt_pk_bf16_f32 v51, v54, v55
	v_cmp_ge_i32_e32 vcc, s10, v46
	s_and_b64 exec, exec, vcc
	global_store_dwordx4 v[60:61], v[48:51], off nt
	s_mov_b64 exec, s[98:99]
	s_andn2_b64 exec, exec, s[4:5]
	s_cbranch_execnz .LBB0_513
